# loop-edge edit: in-proj and out-proj K-loop counter and pointer updates moved ahead of the closing barrier (on top of v10)
# baseline (speedup 1.0000x reference)
; #define PG8_STAGE(bufoff, gbase, voff) do { _Pragma("unroll") for (int _i = 0; _i < 2; ++_i) \
;         __builtin_amdgcn_global_load_lds((const unsigned*)((const char*)(gbase) + (voff)[_i]), (LAS unsigned*)(lds + (bufoff) + ldsw + _i * 8192), 16, 0, 0); } while (0)
; #define PG8_LDA(dst, b, h) do { _Pragma("unroll") for (int m = 0; m < 4; ++m) _Pragma("unroll") for (int k = 0; k < 2; ++k) dst[m][k] = *(const LAS bf16x8*)(lds + PG8_SA(b, h) + aoff + m * 2048 + k * 1024); } while (0)
; #define PG8_LDB(dst, b, h) do { _Pragma("unroll") for (int n = 0; n < 2; ++n) _Pragma("unroll") for (int k = 0; k < 2; ++k) dst[n][k] = *(const LAS bf16x8*)(lds + PG8_SB(b, h) + boff + n * 2048 + k * 1024); } while (0)
; #define PG8_MMA(ai, bj, At, Bt) do { __builtin_amdgcn_s_setprio(1); _Pragma("unroll") for (int m = 0; m < 4; ++m) _Pragma("unroll") for (int n = 0; n < 2; ++n) _Pragma("unroll") for (int k = 0; k < 2; ++k) \
;         acc[ai][bj][m][n] = __builtin_amdgcn_mfma_f32_16x16x32_bf16(Bt[n][k], At[m][k], acc[ai][bj][m][n], 0, 0, 0); __builtin_amdgcn_s_setprio(0); } while (0)
; #define PG8_WAIT_V(n) asm volatile("s_waitcnt vmcnt(" #n ")" ::: "memory")
; #define PG8_WAIT_L(n) asm volatile("s_waitcnt lgkmcnt(" #n ")" ::: "memory")
; #define PG8_BAR __builtin_amdgcn_s_barrier()
; #define PG8_SCHED __builtin_amdgcn_sched_barrier(0)
; template <class Epi, class Sched>
; DI void gemm_phase(LAS unsigned char* lds, const Gemm g, const Sched& S, const Epi& E) {
;     ...
;         for (int t = 0; t < nt; t += 2) {
;             const bool last = (t == nt - 2);
;             const char* a1 = cA + (size_t)(t + 1) * kstep;
;             const char* a2 = last ? nA : cA + (size_t)(t + 2) * kstep; const char* b2 = last ? nB : cB + (size_t)(t + 2) * kstep;
;             const char* a3 = a2 + kstep; const char* b3 = b2 + kstep;
;             PG8_LDB(B0, 0, 0); PG8_LDB(B1, 0, 1); PG8_SCHED; PG8_LDA(At, 0, 0); PG8_STAGE(PG8_SA(1, 1), a1 + hstepA, voffA);
;             PG8_WAIT_V(8); PG8_WAIT_L(0); PG8_BAR; PG8_MMA(0, 0, At, B0); PG8_MMA(0, 1, At, B1); PG8_BAR; PG8_SCHED;
;             PG8_LDA(At, 0, 1); PG8_STAGE(PG8_SB(0, 0), b2, voffB); PG8_STAGE(PG8_SB(0, 1), b2 + hstepB, voffB); PG8_STAGE(PG8_SA(0, 0), a2, voffA);
;             PG8_WAIT_V(8); PG8_WAIT_L(0); PG8_BAR; PG8_MMA(1, 0, At, B0); PG8_MMA(1, 1, At, B1); PG8_BAR; PG8_SCHED;
.LBB0_210:
	s_add_u32 s9, s38, 0xfff80080
	s_addc_u32 s10, s39, -1
	s_add_i32 s11, 0, 0x10000
	s_cmp_eq_u32 s8, 28
	s_cselect_b32 s75, s59, s10
	s_cselect_b32 s74, vcc_lo, s9
	s_cselect_b32 s73, s31, s7
	s_cselect_b32 s72, vcc_hi, s6
	s_add_i32 s9, 0, 0x14000
	v_add_u32_e32 v108, s11, v154
	v_add_u32_e32 v159, s9, v154
	ds_read_b128 v[96:99], v108
	ds_read_b128 v[100:103], v108 offset:1024
	ds_read_b128 v[104:107], v108 offset:2048
	ds_read_b128 v[108:111], v108 offset:3072
	ds_read_b128 v[160:163], v159
	ds_read_b128 v[164:167], v159 offset:1024
	ds_read_b128 v[168:171], v159 offset:2048
	ds_read_b128 v[172:175], v159 offset:3072
	v_lshl_add_u64 v[208:209], s[38:39], 0, v[148:149]
	s_add_i32 m0, s69, 0xc000
	ds_read_b128 v[176:179], v157
	ds_read_b128 v[180:183], v157 offset:1024
	ds_read_b128 v[184:187], v157 offset:2048
	ds_read_b128 v[188:191], v157 offset:3072
	ds_read_b128 v[192:195], v157 offset:4096
	ds_read_b128 v[196:199], v157 offset:5120
	ds_read_b128 v[200:203], v157 offset:6144
	ds_read_b128 v[204:207], v157 offset:7168
	global_load_lds_dwordx4 v[208:209], off
	v_lshl_add_u64 v[208:209], s[38:39], 0, v[150:151]
	s_add_i32 m0, s69, 0xe000
	s_nop 0
	global_load_lds_dwordx4 v[208:209], off
	s_waitcnt vmcnt(8)
	s_waitcnt lgkmcnt(0)
	s_barrier
	s_waitcnt lgkmcnt(0)
	v_mfma_f32_16x16x32_bf16 v[140:143], v[96:99], v[176:179], v[140:143]
	v_mfma_f32_16x16x32_bf16 v[136:139], v[104:107], v[176:179], v[136:139]
	v_mfma_f32_16x16x32_bf16 v[124:127], v[96:99], v[184:187], v[124:127]
	v_mfma_f32_16x16x32_bf16 v[120:123], v[104:107], v[184:187], v[120:123]
	v_mfma_f32_16x16x32_bf16 v[92:95], v[96:99], v[192:195], v[92:95]
	v_mfma_f32_16x16x32_bf16 v[88:91], v[104:107], v[192:195], v[88:91]
	v_mfma_f32_16x16x32_bf16 v[76:79], v[96:99], v[200:203], v[76:79]
	v_mfma_f32_16x16x32_bf16 v[72:75], v[104:107], v[200:203], v[72:75]
	v_mfma_f32_16x16x32_bf16 v[140:143], v[100:103], v[180:183], v[140:143]
	v_mfma_f32_16x16x32_bf16 v[136:139], v[108:111], v[180:183], v[136:139]
	v_mfma_f32_16x16x32_bf16 v[124:127], v[100:103], v[188:191], v[124:127]
	v_mfma_f32_16x16x32_bf16 v[120:123], v[108:111], v[188:191], v[120:123]
	v_mfma_f32_16x16x32_bf16 v[92:95], v[100:103], v[196:199], v[92:95]
	v_mfma_f32_16x16x32_bf16 v[88:91], v[108:111], v[196:199], v[88:91]
	v_mfma_f32_16x16x32_bf16 v[76:79], v[100:103], v[204:207], v[76:79]
	v_mfma_f32_16x16x32_bf16 v[72:75], v[108:111], v[204:207], v[72:75]
	v_mfma_f32_16x16x32_bf16 v[132:135], v[160:163], v[176:179], v[132:135]
	v_mfma_f32_16x16x32_bf16 v[128:131], v[168:171], v[176:179], v[128:131]
	v_mfma_f32_16x16x32_bf16 v[116:119], v[160:163], v[184:187], v[116:119]
	v_mfma_f32_16x16x32_bf16 v[112:115], v[168:171], v[184:187], v[112:115]
	v_mfma_f32_16x16x32_bf16 v[84:87], v[160:163], v[192:195], v[84:87]
	v_mfma_f32_16x16x32_bf16 v[80:83], v[168:171], v[192:195], v[80:83]
	v_mfma_f32_16x16x32_bf16 v[68:71], v[160:163], v[200:203], v[68:71]
	v_mfma_f32_16x16x32_bf16 v[64:67], v[168:171], v[200:203], v[64:67]
	v_mfma_f32_16x16x32_bf16 v[132:135], v[164:167], v[180:183], v[132:135]
	v_mfma_f32_16x16x32_bf16 v[128:131], v[172:175], v[180:183], v[128:131]
	v_mfma_f32_16x16x32_bf16 v[116:119], v[164:167], v[188:191], v[116:119]
	v_mfma_f32_16x16x32_bf16 v[112:115], v[172:175], v[188:191], v[112:115]
	v_mfma_f32_16x16x32_bf16 v[84:87], v[164:167], v[196:199], v[84:87]
	v_mfma_f32_16x16x32_bf16 v[80:83], v[172:175], v[196:199], v[80:83]
	v_mfma_f32_16x16x32_bf16 v[68:71], v[164:167], v[204:207], v[68:71]
	v_mfma_f32_16x16x32_bf16 v[64:67], v[172:175], v[204:207], v[64:67]
	s_barrier
	s_add_i32 s10, s11, s96
	v_lshl_add_u64 v[208:209], s[72:73], 0, v[144:145]
	s_mov_b32 m0, s10
	ds_read_b128 v[176:179], v157 offset:16384
	ds_read_b128 v[180:183], v157 offset:17408
	ds_read_b128 v[184:187], v157 offset:18432
	ds_read_b128 v[188:191], v157 offset:19456
	ds_read_b128 v[192:195], v157 offset:20480
	ds_read_b128 v[196:199], v157 offset:21504
	ds_read_b128 v[200:203], v157 offset:22528
	ds_read_b128 v[204:207], v157 offset:23552
	global_load_lds_dwordx4 v[208:209], off
	s_add_i32 m0, s10, 0x2000
	s_add_u32 s10, s72, 0x80000
	v_lshl_add_u64 v[210:211], s[72:73], 0, v[146:147]
	s_addc_u32 s11, s73, 0
	s_add_i32 s9, s9, s96
	global_load_lds_dwordx4 v[210:211], off
	v_lshl_add_u64 v[212:213], s[10:11], 0, v[144:145]
	s_mov_b32 m0, s9
	v_lshl_add_u64 v[214:215], s[74:75], 0, v[146:147]
	global_load_lds_dwordx4 v[212:213], off
	v_lshl_add_u64 v[212:213], s[10:11], 0, v[146:147]
	s_add_i32 m0, s9, 0x2000
	s_nop 0
	global_load_lds_dwordx4 v[212:213], off
	v_lshl_add_u64 v[212:213], s[74:75], 0, v[144:145]
	s_mov_b32 m0, s69
	s_nop 0
	global_load_lds_dwordx4 v[212:213], off
	s_mov_b32 m0, s71
	s_nop 0
	global_load_lds_dwordx4 v[214:215], off
	s_waitcnt vmcnt(8)
	s_waitcnt lgkmcnt(0)
	s_barrier
; #define PG8_STAGE(bufoff, gbase, voff) do { _Pragma("unroll") for (int _i = 0; _i < 2; ++_i) \
;         __builtin_amdgcn_global_load_lds((const unsigned*)((const char*)(gbase) + (voff)[_i]), (LAS unsigned*)(lds + (bufoff) + ldsw + _i * 8192), 16, 0, 0); } while (0)
; #define PG8_LDA(dst, b, h) do { _Pragma("unroll") for (int m = 0; m < 4; ++m) _Pragma("unroll") for (int k = 0; k < 2; ++k) dst[m][k] = *(const LAS bf16x8*)(lds + PG8_SA(b, h) + aoff + m * 2048 + k * 1024); } while (0)
; #define PG8_LDB(dst, b, h) do { _Pragma("unroll") for (int n = 0; n < 2; ++n) _Pragma("unroll") for (int k = 0; k < 2; ++k) dst[n][k] = *(const LAS bf16x8*)(lds + PG8_SB(b, h) + boff + n * 2048 + k * 1024); } while (0)
; #define PG8_MMA(ai, bj, At, Bt) do { __builtin_amdgcn_s_setprio(1); _Pragma("unroll") for (int m = 0; m < 4; ++m) _Pragma("unroll") for (int n = 0; n < 2; ++n) _Pragma("unroll") for (int k = 0; k < 2; ++k) \
;         acc[ai][bj][m][n] = __builtin_amdgcn_mfma_f32_16x16x32_bf16(Bt[n][k], At[m][k], acc[ai][bj][m][n], 0, 0, 0); __builtin_amdgcn_s_setprio(0); } while (0)
; #define PG8_WAIT_V(n) asm volatile("s_waitcnt vmcnt(" #n ")" ::: "memory")
; #define PG8_WAIT_L(n) asm volatile("s_waitcnt lgkmcnt(" #n ")" ::: "memory")
; #define PG8_BAR __builtin_amdgcn_s_barrier()
; #define PG8_SCHED __builtin_amdgcn_sched_barrier(0)
; template <class Epi, class Sched>
; DI void gemm_phase(LAS unsigned char* lds, const Gemm g, const Sched& S, const Epi& E) {
;     ...
;             PG8_WAIT_V(8); PG8_WAIT_L(0); PG8_BAR; PG8_MMA(1, 0, At, B0); PG8_MMA(1, 1, At, B1); PG8_BAR; PG8_SCHED;
;             PG8_LDB(B0, 1, 0); PG8_LDB(B1, 1, 1); PG8_SCHED; PG8_LDA(At, 1, 0); PG8_STAGE(PG8_SA(0, 1), a2 + hstepA, voffA);
;             PG8_WAIT_V(8); PG8_WAIT_L(0); PG8_BAR; PG8_MMA(0, 0, At, B0); PG8_MMA(0, 1, At, B1); PG8_BAR; PG8_SCHED;
	s_waitcnt lgkmcnt(0)
	v_mfma_f32_16x16x32_bf16 v[60:63], v[96:99], v[176:179], v[60:63]
	v_mfma_f32_16x16x32_bf16 v[56:59], v[104:107], v[176:179], v[56:59]
	v_mfma_f32_16x16x32_bf16 v[44:47], v[96:99], v[184:187], v[44:47]
	v_mfma_f32_16x16x32_bf16 v[40:43], v[104:107], v[184:187], v[40:43]
	v_mfma_f32_16x16x32_bf16 v[28:31], v[96:99], v[192:195], v[28:31]
	v_mfma_f32_16x16x32_bf16 v[24:27], v[104:107], v[192:195], v[24:27]
	v_mfma_f32_16x16x32_bf16 v[12:15], v[96:99], v[200:203], v[12:15]
	v_mfma_f32_16x16x32_bf16 v[8:11], v[104:107], v[200:203], v[8:11]
	v_mfma_f32_16x16x32_bf16 v[60:63], v[100:103], v[180:183], v[60:63]
	v_mfma_f32_16x16x32_bf16 v[56:59], v[108:111], v[180:183], v[56:59]
	v_mfma_f32_16x16x32_bf16 v[44:47], v[100:103], v[188:191], v[44:47]
	v_mfma_f32_16x16x32_bf16 v[40:43], v[108:111], v[188:191], v[40:43]
	v_mfma_f32_16x16x32_bf16 v[28:31], v[100:103], v[196:199], v[28:31]
	v_mfma_f32_16x16x32_bf16 v[24:27], v[108:111], v[196:199], v[24:27]
	v_mfma_f32_16x16x32_bf16 v[12:15], v[100:103], v[204:207], v[12:15]
	v_mfma_f32_16x16x32_bf16 v[8:11], v[108:111], v[204:207], v[8:11]
	v_mfma_f32_16x16x32_bf16 v[52:55], v[160:163], v[176:179], v[52:55]
	v_mfma_f32_16x16x32_bf16 v[48:51], v[168:171], v[176:179], v[48:51]
	v_mfma_f32_16x16x32_bf16 v[36:39], v[160:163], v[184:187], v[36:39]
	v_mfma_f32_16x16x32_bf16 v[32:35], v[168:171], v[184:187], v[32:35]
	v_mfma_f32_16x16x32_bf16 v[20:23], v[160:163], v[192:195], v[20:23]
	v_mfma_f32_16x16x32_bf16 v[16:19], v[168:171], v[192:195], v[16:19]
	v_mfma_f32_16x16x32_bf16 v[4:7], v[160:163], v[200:203], v[4:7]
	v_mfma_f32_16x16x32_bf16 v[0:3], v[168:171], v[200:203], v[0:3]
	v_mfma_f32_16x16x32_bf16 v[52:55], v[164:167], v[180:183], v[52:55]
	v_mfma_f32_16x16x32_bf16 v[48:51], v[172:175], v[180:183], v[48:51]
	v_mfma_f32_16x16x32_bf16 v[36:39], v[164:167], v[188:191], v[36:39]
	v_mfma_f32_16x16x32_bf16 v[32:35], v[172:175], v[188:191], v[32:35]
	v_mfma_f32_16x16x32_bf16 v[20:23], v[164:167], v[196:199], v[20:23]
	v_mfma_f32_16x16x32_bf16 v[16:19], v[172:175], v[196:199], v[16:19]
	v_mfma_f32_16x16x32_bf16 v[4:7], v[164:167], v[204:207], v[4:7]
	v_mfma_f32_16x16x32_bf16 v[0:3], v[172:175], v[204:207], v[0:3]
	s_barrier
	s_add_i32 s9, 0, 0x18000
	s_add_i32 s12, 0, 0x1c000
	v_add_u32_e32 v108, s9, v154
	v_add_u32_e32 v159, s12, v154
	ds_read_b128 v[96:99], v108
	ds_read_b128 v[100:103], v108 offset:1024
	ds_read_b128 v[104:107], v108 offset:2048
	ds_read_b128 v[108:111], v108 offset:3072
	ds_read_b128 v[160:163], v159
	ds_read_b128 v[164:167], v159 offset:1024
	ds_read_b128 v[168:171], v159 offset:2048
	ds_read_b128 v[172:175], v159 offset:3072
	s_add_u32 s10, s74, 0x80000
	s_addc_u32 s11, s75, 0
	s_mov_b32 m0, s97
	v_lshl_add_u64 v[216:217], s[10:11], 0, v[144:145]
	ds_read_b128 v[176:179], v157 offset:32768
	ds_read_b128 v[180:183], v157 offset:33792
	ds_read_b128 v[184:187], v157 offset:34816
	ds_read_b128 v[188:191], v157 offset:35840
	ds_read_b128 v[192:195], v157 offset:36864
	ds_read_b128 v[196:199], v157 offset:37888
	ds_read_b128 v[200:203], v157 offset:38912
	ds_read_b128 v[204:207], v157 offset:39936
	global_load_lds_dwordx4 v[216:217], off
	v_lshl_add_u64 v[216:217], s[10:11], 0, v[146:147]
	s_mov_b32 m0, s98
	s_nop 0
	global_load_lds_dwordx4 v[216:217], off
	s_waitcnt vmcnt(8)
	s_waitcnt lgkmcnt(0)
	s_barrier
	s_waitcnt lgkmcnt(0)
	v_mfma_f32_16x16x32_bf16 v[140:143], v[96:99], v[176:179], v[140:143]
	v_mfma_f32_16x16x32_bf16 v[136:139], v[104:107], v[176:179], v[136:139]
	v_mfma_f32_16x16x32_bf16 v[124:127], v[96:99], v[184:187], v[124:127]
	v_mfma_f32_16x16x32_bf16 v[120:123], v[104:107], v[184:187], v[120:123]
	v_mfma_f32_16x16x32_bf16 v[92:95], v[96:99], v[192:195], v[92:95]
	v_mfma_f32_16x16x32_bf16 v[88:91], v[104:107], v[192:195], v[88:91]
	v_mfma_f32_16x16x32_bf16 v[76:79], v[96:99], v[200:203], v[76:79]
	v_mfma_f32_16x16x32_bf16 v[72:75], v[104:107], v[200:203], v[72:75]
	v_mfma_f32_16x16x32_bf16 v[140:143], v[100:103], v[180:183], v[140:143]
	v_mfma_f32_16x16x32_bf16 v[136:139], v[108:111], v[180:183], v[136:139]
	v_mfma_f32_16x16x32_bf16 v[124:127], v[100:103], v[188:191], v[124:127]
	v_mfma_f32_16x16x32_bf16 v[120:123], v[108:111], v[188:191], v[120:123]
	v_mfma_f32_16x16x32_bf16 v[92:95], v[100:103], v[196:199], v[92:95]
	v_mfma_f32_16x16x32_bf16 v[88:91], v[108:111], v[196:199], v[88:91]
	v_mfma_f32_16x16x32_bf16 v[76:79], v[100:103], v[204:207], v[76:79]
	v_mfma_f32_16x16x32_bf16 v[72:75], v[108:111], v[204:207], v[72:75]
	v_mfma_f32_16x16x32_bf16 v[132:135], v[160:163], v[176:179], v[132:135]
	v_mfma_f32_16x16x32_bf16 v[128:131], v[168:171], v[176:179], v[128:131]
	v_mfma_f32_16x16x32_bf16 v[116:119], v[160:163], v[184:187], v[116:119]
	v_mfma_f32_16x16x32_bf16 v[112:115], v[168:171], v[184:187], v[112:115]
	v_mfma_f32_16x16x32_bf16 v[84:87], v[160:163], v[192:195], v[84:87]
	v_mfma_f32_16x16x32_bf16 v[80:83], v[168:171], v[192:195], v[80:83]
	v_mfma_f32_16x16x32_bf16 v[68:71], v[160:163], v[200:203], v[68:71]
	v_mfma_f32_16x16x32_bf16 v[64:67], v[168:171], v[200:203], v[64:67]
	v_mfma_f32_16x16x32_bf16 v[132:135], v[164:167], v[180:183], v[132:135]
	v_mfma_f32_16x16x32_bf16 v[128:131], v[172:175], v[180:183], v[128:131]
	v_mfma_f32_16x16x32_bf16 v[116:119], v[164:167], v[188:191], v[116:119]
	v_mfma_f32_16x16x32_bf16 v[112:115], v[172:175], v[188:191], v[112:115]
	v_mfma_f32_16x16x32_bf16 v[84:87], v[164:167], v[196:199], v[84:87]
	v_mfma_f32_16x16x32_bf16 v[80:83], v[172:175], v[196:199], v[80:83]
	v_mfma_f32_16x16x32_bf16 v[68:71], v[164:167], v[204:207], v[68:71]
	v_mfma_f32_16x16x32_bf16 v[64:67], v[172:175], v[204:207], v[64:67]
	s_barrier
; #define PG8_STAGE(bufoff, gbase, voff) do { _Pragma("unroll") for (int _i = 0; _i < 2; ++_i) \
;         __builtin_amdgcn_global_load_lds((const unsigned*)((const char*)(gbase) + (voff)[_i]), (LAS unsigned*)(lds + (bufoff) + ldsw + _i * 8192), 16, 0, 0); } while (0)
; #define PG8_LDA(dst, b, h) do { _Pragma("unroll") for (int m = 0; m < 4; ++m) _Pragma("unroll") for (int k = 0; k < 2; ++k) dst[m][k] = *(const LAS bf16x8*)(lds + PG8_SA(b, h) + aoff + m * 2048 + k * 1024); } while (0)
; #define PG8_MMA(ai, bj, At, Bt) do { __builtin_amdgcn_s_setprio(1); _Pragma("unroll") for (int m = 0; m < 4; ++m) _Pragma("unroll") for (int n = 0; n < 2; ++n) _Pragma("unroll") for (int k = 0; k < 2; ++k) \
;         acc[ai][bj][m][n] = __builtin_amdgcn_mfma_f32_16x16x32_bf16(Bt[n][k], At[m][k], acc[ai][bj][m][n], 0, 0, 0); __builtin_amdgcn_s_setprio(0); } while (0)
; #define PG8_WAIT_V(n) asm volatile("s_waitcnt vmcnt(" #n ")" ::: "memory")
; #define PG8_WAIT_L(n) asm volatile("s_waitcnt lgkmcnt(" #n ")" ::: "memory")
; #define PG8_BAR __builtin_amdgcn_s_barrier()
; #define PG8_SCHED __builtin_amdgcn_sched_barrier(0)
; template <class Epi, class Sched>
; DI void gemm_phase(LAS unsigned char* lds, const Gemm g, const Sched& S, const Epi& E) {
;     ...
;             PG8_LDA(At, 1, 1); PG8_STAGE(PG8_SB(1, 0), b3, voffB); PG8_STAGE(PG8_SB(1, 1), b3 + hstepB, voffB); PG8_STAGE(PG8_SA(1, 0), a3, voffA);
;             PG8_WAIT_V(8); PG8_WAIT_L(0); PG8_BAR; PG8_MMA(1, 0, At, B0); PG8_MMA(1, 1, At, B1); PG8_BAR; PG8_SCHED;
;         }
;         if (wr == 0) PG8_BAR;
	s_add_i32 s9, s9, s96
	v_lshl_add_u64 v[208:209], v[208:209], 0, s[28:29]
	s_mov_b32 m0, s9
	ds_read_b128 v[176:179], v157 offset:49152
	ds_read_b128 v[180:183], v157 offset:50176
	ds_read_b128 v[184:187], v157 offset:51200
	ds_read_b128 v[188:191], v157 offset:52224
	ds_read_b128 v[192:195], v157 offset:53248
	ds_read_b128 v[196:199], v157 offset:54272
	ds_read_b128 v[200:203], v157 offset:55296
	ds_read_b128 v[204:207], v157 offset:56320
	global_load_lds_dwordx4 v[208:209], off
	s_add_i32 m0, s9, 0x2000
	s_add_u32 s10, s72, 0x80080
	v_lshl_add_u64 v[208:209], v[210:211], 0, s[28:29]
	s_addc_u32 s11, s73, 0
	s_add_i32 s9, s12, s96
	global_load_lds_dwordx4 v[208:209], off
	v_lshl_add_u64 v[208:209], s[10:11], 0, v[144:145]
	s_mov_b32 m0, s9
	s_nop 0
	global_load_lds_dwordx4 v[208:209], off
	v_lshl_add_u64 v[208:209], s[10:11], 0, v[146:147]
	s_add_i32 m0, s9, 0x2000
	s_nop 0
	global_load_lds_dwordx4 v[208:209], off
	v_lshl_add_u64 v[208:209], v[212:213], 0, s[28:29]
	s_mov_b32 m0, s0
	s_nop 0
	global_load_lds_dwordx4 v[208:209], off
	v_lshl_add_u64 v[208:209], v[214:215], 0, s[28:29]
	s_mov_b32 m0, s1
	s_nop 0
	global_load_lds_dwordx4 v[208:209], off
	s_waitcnt vmcnt(8)
	s_waitcnt lgkmcnt(0)
	s_barrier
	s_waitcnt lgkmcnt(0)
	v_mfma_f32_16x16x32_bf16 v[60:63], v[96:99], v[176:179], v[60:63]
	v_mfma_f32_16x16x32_bf16 v[56:59], v[104:107], v[176:179], v[56:59]
	v_mfma_f32_16x16x32_bf16 v[44:47], v[96:99], v[184:187], v[44:47]
	v_mfma_f32_16x16x32_bf16 v[40:43], v[104:107], v[184:187], v[40:43]
	v_mfma_f32_16x16x32_bf16 v[28:31], v[96:99], v[192:195], v[28:31]
	v_mfma_f32_16x16x32_bf16 v[24:27], v[104:107], v[192:195], v[24:27]
	v_mfma_f32_16x16x32_bf16 v[12:15], v[96:99], v[200:203], v[12:15]
	v_mfma_f32_16x16x32_bf16 v[8:11], v[104:107], v[200:203], v[8:11]
	v_mfma_f32_16x16x32_bf16 v[60:63], v[100:103], v[180:183], v[60:63]
	v_mfma_f32_16x16x32_bf16 v[56:59], v[108:111], v[180:183], v[56:59]
	v_mfma_f32_16x16x32_bf16 v[44:47], v[100:103], v[188:191], v[44:47]
	v_mfma_f32_16x16x32_bf16 v[40:43], v[108:111], v[188:191], v[40:43]
	v_mfma_f32_16x16x32_bf16 v[28:31], v[100:103], v[196:199], v[28:31]
	v_mfma_f32_16x16x32_bf16 v[24:27], v[108:111], v[196:199], v[24:27]
	v_mfma_f32_16x16x32_bf16 v[12:15], v[100:103], v[204:207], v[12:15]
	v_mfma_f32_16x16x32_bf16 v[8:11], v[108:111], v[204:207], v[8:11]
	v_mfma_f32_16x16x32_bf16 v[52:55], v[160:163], v[176:179], v[52:55]
	v_mfma_f32_16x16x32_bf16 v[48:51], v[168:171], v[176:179], v[48:51]
	v_mfma_f32_16x16x32_bf16 v[36:39], v[160:163], v[184:187], v[36:39]
	v_mfma_f32_16x16x32_bf16 v[32:35], v[168:171], v[184:187], v[32:35]
	v_mfma_f32_16x16x32_bf16 v[20:23], v[160:163], v[192:195], v[20:23]
	v_mfma_f32_16x16x32_bf16 v[16:19], v[168:171], v[192:195], v[16:19]
	v_mfma_f32_16x16x32_bf16 v[4:7], v[160:163], v[200:203], v[4:7]
	v_mfma_f32_16x16x32_bf16 v[0:3], v[168:171], v[200:203], v[0:3]
	v_mfma_f32_16x16x32_bf16 v[52:55], v[164:167], v[180:183], v[52:55]
	v_mfma_f32_16x16x32_bf16 v[48:51], v[172:175], v[180:183], v[48:51]
	v_mfma_f32_16x16x32_bf16 v[36:39], v[164:167], v[188:191], v[36:39]
	v_mfma_f32_16x16x32_bf16 v[32:35], v[172:175], v[188:191], v[32:35]
	v_mfma_f32_16x16x32_bf16 v[20:23], v[164:167], v[196:199], v[20:23]
	v_mfma_f32_16x16x32_bf16 v[16:19], v[172:175], v[196:199], v[16:19]
	v_mfma_f32_16x16x32_bf16 v[4:7], v[164:167], v[204:207], v[4:7]
	v_mfma_f32_16x16x32_bf16 v[0:3], v[172:175], v[204:207], v[0:3]
	s_add_i32 s8, s8, 2
	s_add_u32 s38, s38, 0x100
	s_addc_u32 s39, s39, 0
	s_add_u32 s6, s6, 0x100
	s_addc_u32 s7, s7, 0
	s_barrier
	s_cmp_gt_u32 s8, 29
	s_cbranch_scc0 .LBB0_210
	s_and_b64 vcc, exec, s[60:61]
	s_cbranch_vccz .LBB0_213
	s_barrier

; #define PG8_STAGE(bufoff, gbase, voff) do { _Pragma("unroll") for (int _i = 0; _i < 2; ++_i) \
;         __builtin_amdgcn_global_load_lds((const unsigned*)((const char*)(gbase) + (voff)[_i]), (LAS unsigned*)(lds + (bufoff) + ldsw + _i * 8192), 16, 0, 0); } while (0)
; #define PG8_LDA(dst, b, h) do { _Pragma("unroll") for (int m = 0; m < 4; ++m) _Pragma("unroll") for (int k = 0; k < 2; ++k) dst[m][k] = *(const LAS bf16x8*)(lds + PG8_SA(b, h) + aoff + m * 2048 + k * 1024); } while (0)
; #define PG8_LDB(dst, b, h) do { _Pragma("unroll") for (int n = 0; n < 2; ++n) _Pragma("unroll") for (int k = 0; k < 2; ++k) dst[n][k] = *(const LAS bf16x8*)(lds + PG8_SB(b, h) + boff + n * 2048 + k * 1024); } while (0)
; #define PG8_MMA(ai, bj, At, Bt) do { __builtin_amdgcn_s_setprio(1); _Pragma("unroll") for (int m = 0; m < 4; ++m) _Pragma("unroll") for (int n = 0; n < 2; ++n) _Pragma("unroll") for (int k = 0; k < 2; ++k) \
;         acc[ai][bj][m][n] = __builtin_amdgcn_mfma_f32_16x16x32_bf16(Bt[n][k], At[m][k], acc[ai][bj][m][n], 0, 0, 0); __builtin_amdgcn_s_setprio(0); } while (0)
; #define PG8_WAIT_V(n) asm volatile("s_waitcnt vmcnt(" #n ")" ::: "memory")
; #define PG8_WAIT_L(n) asm volatile("s_waitcnt lgkmcnt(" #n ")" ::: "memory")
; #define PG8_BAR __builtin_amdgcn_s_barrier()
; #define PG8_SCHED __builtin_amdgcn_sched_barrier(0)
; template <class Epi, class Sched>
; DI void gemm_phase(LAS unsigned char* lds, const Gemm g, const Sched& S, const Epi& E) {
;     ...
;         for (int t = 0; t < nt; t += 2) {
;             const bool last = (t == nt - 2);
;             const char* a1 = cA + (size_t)(t + 1) * kstep;
;             const char* a2 = last ? nA : cA + (size_t)(t + 2) * kstep; const char* b2 = last ? nB : cB + (size_t)(t + 2) * kstep;
;             const char* a3 = a2 + kstep; const char* b3 = b2 + kstep;
;             PG8_LDB(B0, 0, 0); PG8_LDB(B1, 0, 1); PG8_SCHED; PG8_LDA(At, 0, 0); PG8_STAGE(PG8_SA(1, 1), a1 + hstepA, voffA);
;             PG8_WAIT_V(8); PG8_WAIT_L(0); PG8_BAR; PG8_MMA(0, 0, At, B0); PG8_MMA(0, 1, At, B1); PG8_BAR; PG8_SCHED;
;             PG8_LDA(At, 0, 1); PG8_STAGE(PG8_SB(0, 0), b2, voffB); PG8_STAGE(PG8_SB(0, 1), b2 + hstepB, voffB); PG8_STAGE(PG8_SA(0, 0), a2, voffA);
;             PG8_WAIT_V(8); PG8_WAIT_L(0); PG8_BAR; PG8_MMA(1, 0, At, B0); PG8_MMA(1, 1, At, B1); PG8_BAR; PG8_SCHED;
.LBB0_417:
	s_add_u32 s9, s66, 0xfff80080
	s_addc_u32 s10, s67, -1
	s_add_i32 s11, 0, 0x10000
	s_cmp_eq_u32 s8, 28
	s_cselect_b32 s71, s31, s10
	s_cselect_b32 s70, s37, s9
	s_cselect_b32 s69, s39, s7
	s_cselect_b32 s68, s59, s6
	s_add_i32 s9, 0, 0x14000
	v_add_u32_e32 v72, s11, v167
	v_add_u32_e32 v162, s9, v167
	ds_read_b128 v[56:59], v72
	ds_read_b128 v[60:63], v72 offset:1024
	ds_read_b128 v[68:71], v72 offset:2048
	ds_read_b128 v[72:75], v72 offset:3072
	ds_read_b128 v[144:147], v162
	ds_read_b128 v[148:151], v162 offset:1024
	ds_read_b128 v[158:161], v162 offset:2048
	ds_read_b128 v[162:165], v162 offset:3072
	v_lshl_add_u64 v[202:203], s[66:67], 0, v[154:155]
	s_add_i32 m0, s5, 0xc000
	ds_read_b128 v[170:173], v169
	ds_read_b128 v[174:177], v169 offset:1024
	ds_read_b128 v[178:181], v169 offset:2048
	ds_read_b128 v[182:185], v169 offset:3072
	ds_read_b128 v[186:189], v169 offset:4096
	ds_read_b128 v[190:193], v169 offset:5120
	ds_read_b128 v[194:197], v169 offset:6144
	ds_read_b128 v[198:201], v169 offset:7168
	global_load_lds_dwordx4 v[202:203], off
	v_lshl_add_u64 v[202:203], s[66:67], 0, v[156:157]
	s_add_i32 m0, s5, 0xe000
	s_nop 0
	global_load_lds_dwordx4 v[202:203], off
	s_waitcnt vmcnt(8)
	s_waitcnt lgkmcnt(0)
	s_barrier
	s_waitcnt lgkmcnt(0)
	v_mfma_f32_16x16x32_bf16 v[140:143], v[56:59], v[170:173], v[140:143]
	v_mfma_f32_16x16x32_bf16 v[136:139], v[68:71], v[170:173], v[136:139]
	v_mfma_f32_16x16x32_bf16 v[124:127], v[56:59], v[178:181], v[124:127]
	v_mfma_f32_16x16x32_bf16 v[120:123], v[68:71], v[178:181], v[120:123]
	v_mfma_f32_16x16x32_bf16 v[108:111], v[56:59], v[186:189], v[108:111]
	v_mfma_f32_16x16x32_bf16 v[104:107], v[68:71], v[186:189], v[104:107]
	v_mfma_f32_16x16x32_bf16 v[92:95], v[56:59], v[194:197], v[92:95]
	v_mfma_f32_16x16x32_bf16 v[88:91], v[68:71], v[194:197], v[88:91]
	v_mfma_f32_16x16x32_bf16 v[140:143], v[60:63], v[174:177], v[140:143]
	v_mfma_f32_16x16x32_bf16 v[136:139], v[72:75], v[174:177], v[136:139]
	v_mfma_f32_16x16x32_bf16 v[124:127], v[60:63], v[182:185], v[124:127]
	v_mfma_f32_16x16x32_bf16 v[120:123], v[72:75], v[182:185], v[120:123]
	v_mfma_f32_16x16x32_bf16 v[108:111], v[60:63], v[190:193], v[108:111]
	v_mfma_f32_16x16x32_bf16 v[104:107], v[72:75], v[190:193], v[104:107]
	v_mfma_f32_16x16x32_bf16 v[92:95], v[60:63], v[198:201], v[92:95]
	v_mfma_f32_16x16x32_bf16 v[88:91], v[72:75], v[198:201], v[88:91]
	v_mfma_f32_16x16x32_bf16 v[132:135], v[144:147], v[170:173], v[132:135]
	v_mfma_f32_16x16x32_bf16 v[128:131], v[158:161], v[170:173], v[128:131]
	v_mfma_f32_16x16x32_bf16 v[116:119], v[144:147], v[178:181], v[116:119]
	v_mfma_f32_16x16x32_bf16 v[112:115], v[158:161], v[178:181], v[112:115]
	v_mfma_f32_16x16x32_bf16 v[100:103], v[144:147], v[186:189], v[100:103]
	v_mfma_f32_16x16x32_bf16 v[96:99], v[158:161], v[186:189], v[96:99]
	v_mfma_f32_16x16x32_bf16 v[84:87], v[144:147], v[194:197], v[84:87]
	v_mfma_f32_16x16x32_bf16 v[80:83], v[158:161], v[194:197], v[80:83]
	v_mfma_f32_16x16x32_bf16 v[132:135], v[148:151], v[174:177], v[132:135]
	v_mfma_f32_16x16x32_bf16 v[128:131], v[162:165], v[174:177], v[128:131]
	v_mfma_f32_16x16x32_bf16 v[116:119], v[148:151], v[182:185], v[116:119]
	v_mfma_f32_16x16x32_bf16 v[112:115], v[162:165], v[182:185], v[112:115]
	v_mfma_f32_16x16x32_bf16 v[100:103], v[148:151], v[190:193], v[100:103]
	v_mfma_f32_16x16x32_bf16 v[96:99], v[162:165], v[190:193], v[96:99]
	v_mfma_f32_16x16x32_bf16 v[84:87], v[148:151], v[198:201], v[84:87]
	v_mfma_f32_16x16x32_bf16 v[80:83], v[162:165], v[198:201], v[80:83]
	s_barrier
	s_add_i32 s10, s11, s4
	v_lshl_add_u64 v[202:203], s[68:69], 0, v[222:223]
	s_mov_b32 m0, s10
	ds_read_b128 v[170:173], v169 offset:16384
	ds_read_b128 v[174:177], v169 offset:17408
	ds_read_b128 v[178:181], v169 offset:18432
	ds_read_b128 v[182:185], v169 offset:19456
	ds_read_b128 v[186:189], v169 offset:20480
	ds_read_b128 v[190:193], v169 offset:21504
	ds_read_b128 v[194:197], v169 offset:22528
	ds_read_b128 v[198:201], v169 offset:23552
	global_load_lds_dwordx4 v[202:203], off
	s_add_i32 m0, s10, 0x2000
	s_add_u32 s10, s68, 0x80000
	v_lshl_add_u64 v[204:205], s[68:69], 0, v[152:153]
	s_addc_u32 s11, s69, 0
	s_add_i32 s9, s9, s4
	global_load_lds_dwordx4 v[204:205], off
	v_lshl_add_u64 v[206:207], s[10:11], 0, v[222:223]
	s_mov_b32 m0, s9
	v_lshl_add_u64 v[208:209], s[70:71], 0, v[152:153]
	global_load_lds_dwordx4 v[206:207], off
	v_lshl_add_u64 v[206:207], s[10:11], 0, v[152:153]
	s_add_i32 m0, s9, 0x2000
	s_nop 0
	global_load_lds_dwordx4 v[206:207], off
	v_lshl_add_u64 v[206:207], s[70:71], 0, v[222:223]
	s_mov_b32 m0, s5
	s_nop 0
	global_load_lds_dwordx4 v[206:207], off
	s_mov_b32 m0, s72
	s_nop 0
	global_load_lds_dwordx4 v[208:209], off
	s_waitcnt vmcnt(8)
	s_waitcnt lgkmcnt(0)
	s_barrier
; #define PG8_STAGE(bufoff, gbase, voff) do { _Pragma("unroll") for (int _i = 0; _i < 2; ++_i) \
;         __builtin_amdgcn_global_load_lds((const unsigned*)((const char*)(gbase) + (voff)[_i]), (LAS unsigned*)(lds + (bufoff) + ldsw + _i * 8192), 16, 0, 0); } while (0)
; #define PG8_LDA(dst, b, h) do { _Pragma("unroll") for (int m = 0; m < 4; ++m) _Pragma("unroll") for (int k = 0; k < 2; ++k) dst[m][k] = *(const LAS bf16x8*)(lds + PG8_SA(b, h) + aoff + m * 2048 + k * 1024); } while (0)
; #define PG8_LDB(dst, b, h) do { _Pragma("unroll") for (int n = 0; n < 2; ++n) _Pragma("unroll") for (int k = 0; k < 2; ++k) dst[n][k] = *(const LAS bf16x8*)(lds + PG8_SB(b, h) + boff + n * 2048 + k * 1024); } while (0)
; #define PG8_MMA(ai, bj, At, Bt) do { __builtin_amdgcn_s_setprio(1); _Pragma("unroll") for (int m = 0; m < 4; ++m) _Pragma("unroll") for (int n = 0; n < 2; ++n) _Pragma("unroll") for (int k = 0; k < 2; ++k) \
;         acc[ai][bj][m][n] = __builtin_amdgcn_mfma_f32_16x16x32_bf16(Bt[n][k], At[m][k], acc[ai][bj][m][n], 0, 0, 0); __builtin_amdgcn_s_setprio(0); } while (0)
; #define PG8_WAIT_V(n) asm volatile("s_waitcnt vmcnt(" #n ")" ::: "memory")
; #define PG8_WAIT_L(n) asm volatile("s_waitcnt lgkmcnt(" #n ")" ::: "memory")
; #define PG8_BAR __builtin_amdgcn_s_barrier()
; #define PG8_SCHED __builtin_amdgcn_sched_barrier(0)
; template <class Epi, class Sched>
; DI void gemm_phase(LAS unsigned char* lds, const Gemm g, const Sched& S, const Epi& E) {
;     ...
;             PG8_WAIT_V(8); PG8_WAIT_L(0); PG8_BAR; PG8_MMA(1, 0, At, B0); PG8_MMA(1, 1, At, B1); PG8_BAR; PG8_SCHED;
;             PG8_LDB(B0, 1, 0); PG8_LDB(B1, 1, 1); PG8_SCHED; PG8_LDA(At, 1, 0); PG8_STAGE(PG8_SA(0, 1), a2 + hstepA, voffA);
;             PG8_WAIT_V(8); PG8_WAIT_L(0); PG8_BAR; PG8_MMA(0, 0, At, B0); PG8_MMA(0, 1, At, B1); PG8_BAR; PG8_SCHED;
	s_waitcnt lgkmcnt(0)
	v_mfma_f32_16x16x32_bf16 v[76:79], v[56:59], v[170:173], v[76:79]
	v_mfma_f32_16x16x32_bf16 v[64:67], v[68:71], v[170:173], v[64:67]
	v_mfma_f32_16x16x32_bf16 v[44:47], v[56:59], v[178:181], v[44:47]
	v_mfma_f32_16x16x32_bf16 v[40:43], v[68:71], v[178:181], v[40:43]
	v_mfma_f32_16x16x32_bf16 v[28:31], v[56:59], v[186:189], v[28:31]
	v_mfma_f32_16x16x32_bf16 v[24:27], v[68:71], v[186:189], v[24:27]
	v_mfma_f32_16x16x32_bf16 v[12:15], v[56:59], v[194:197], v[12:15]
	v_mfma_f32_16x16x32_bf16 v[8:11], v[68:71], v[194:197], v[8:11]
	v_mfma_f32_16x16x32_bf16 v[76:79], v[60:63], v[174:177], v[76:79]
	v_mfma_f32_16x16x32_bf16 v[64:67], v[72:75], v[174:177], v[64:67]
	v_mfma_f32_16x16x32_bf16 v[44:47], v[60:63], v[182:185], v[44:47]
	v_mfma_f32_16x16x32_bf16 v[40:43], v[72:75], v[182:185], v[40:43]
	v_mfma_f32_16x16x32_bf16 v[28:31], v[60:63], v[190:193], v[28:31]
	v_mfma_f32_16x16x32_bf16 v[24:27], v[72:75], v[190:193], v[24:27]
	v_mfma_f32_16x16x32_bf16 v[12:15], v[60:63], v[198:201], v[12:15]
	v_mfma_f32_16x16x32_bf16 v[8:11], v[72:75], v[198:201], v[8:11]
	v_mfma_f32_16x16x32_bf16 v[52:55], v[144:147], v[170:173], v[52:55]
	v_mfma_f32_16x16x32_bf16 v[48:51], v[158:161], v[170:173], v[48:51]
	v_mfma_f32_16x16x32_bf16 v[36:39], v[144:147], v[178:181], v[36:39]
	v_mfma_f32_16x16x32_bf16 v[32:35], v[158:161], v[178:181], v[32:35]
	v_mfma_f32_16x16x32_bf16 v[20:23], v[144:147], v[186:189], v[20:23]
	v_mfma_f32_16x16x32_bf16 v[16:19], v[158:161], v[186:189], v[16:19]
	v_mfma_f32_16x16x32_bf16 v[4:7], v[144:147], v[194:197], v[4:7]
	v_mfma_f32_16x16x32_bf16 v[0:3], v[158:161], v[194:197], v[0:3]
	v_mfma_f32_16x16x32_bf16 v[52:55], v[148:151], v[174:177], v[52:55]
	v_mfma_f32_16x16x32_bf16 v[48:51], v[162:165], v[174:177], v[48:51]
	v_mfma_f32_16x16x32_bf16 v[36:39], v[148:151], v[182:185], v[36:39]
	v_mfma_f32_16x16x32_bf16 v[32:35], v[162:165], v[182:185], v[32:35]
	v_mfma_f32_16x16x32_bf16 v[20:23], v[148:151], v[190:193], v[20:23]
	v_mfma_f32_16x16x32_bf16 v[16:19], v[162:165], v[190:193], v[16:19]
	v_mfma_f32_16x16x32_bf16 v[4:7], v[148:151], v[198:201], v[4:7]
	v_mfma_f32_16x16x32_bf16 v[0:3], v[162:165], v[198:201], v[0:3]
	s_barrier
	s_add_i32 s9, 0, 0x18000
	s_add_i32 s12, 0, 0x1c000
	v_add_u32_e32 v72, s9, v167
	v_add_u32_e32 v162, s12, v167
	ds_read_b128 v[56:59], v72
	ds_read_b128 v[60:63], v72 offset:1024
	ds_read_b128 v[68:71], v72 offset:2048
	ds_read_b128 v[72:75], v72 offset:3072
	ds_read_b128 v[144:147], v162
	ds_read_b128 v[148:151], v162 offset:1024
	ds_read_b128 v[158:161], v162 offset:2048
	ds_read_b128 v[162:165], v162 offset:3072
	s_add_u32 s10, s70, 0x80000
	s_addc_u32 s11, s71, 0
	s_mov_b32 m0, s73
	v_lshl_add_u64 v[210:211], s[10:11], 0, v[222:223]
	ds_read_b128 v[170:173], v169 offset:32768
	ds_read_b128 v[174:177], v169 offset:33792
	ds_read_b128 v[178:181], v169 offset:34816
	ds_read_b128 v[182:185], v169 offset:35840
	ds_read_b128 v[186:189], v169 offset:36864
	ds_read_b128 v[190:193], v169 offset:37888
	ds_read_b128 v[194:197], v169 offset:38912
	ds_read_b128 v[198:201], v169 offset:39936
	global_load_lds_dwordx4 v[210:211], off
	v_lshl_add_u64 v[210:211], s[10:11], 0, v[152:153]
	s_mov_b32 m0, s74
	s_nop 0
	global_load_lds_dwordx4 v[210:211], off
	s_waitcnt vmcnt(8)
	s_waitcnt lgkmcnt(0)
	s_barrier
	s_waitcnt lgkmcnt(0)
	v_mfma_f32_16x16x32_bf16 v[140:143], v[56:59], v[170:173], v[140:143]
	v_mfma_f32_16x16x32_bf16 v[136:139], v[68:71], v[170:173], v[136:139]
	v_mfma_f32_16x16x32_bf16 v[124:127], v[56:59], v[178:181], v[124:127]
	v_mfma_f32_16x16x32_bf16 v[120:123], v[68:71], v[178:181], v[120:123]
	v_mfma_f32_16x16x32_bf16 v[108:111], v[56:59], v[186:189], v[108:111]
	v_mfma_f32_16x16x32_bf16 v[104:107], v[68:71], v[186:189], v[104:107]
	v_mfma_f32_16x16x32_bf16 v[92:95], v[56:59], v[194:197], v[92:95]
	v_mfma_f32_16x16x32_bf16 v[88:91], v[68:71], v[194:197], v[88:91]
	v_mfma_f32_16x16x32_bf16 v[140:143], v[60:63], v[174:177], v[140:143]
	v_mfma_f32_16x16x32_bf16 v[136:139], v[72:75], v[174:177], v[136:139]
	v_mfma_f32_16x16x32_bf16 v[124:127], v[60:63], v[182:185], v[124:127]
	v_mfma_f32_16x16x32_bf16 v[120:123], v[72:75], v[182:185], v[120:123]
	v_mfma_f32_16x16x32_bf16 v[108:111], v[60:63], v[190:193], v[108:111]
	v_mfma_f32_16x16x32_bf16 v[104:107], v[72:75], v[190:193], v[104:107]
	v_mfma_f32_16x16x32_bf16 v[92:95], v[60:63], v[198:201], v[92:95]
	v_mfma_f32_16x16x32_bf16 v[88:91], v[72:75], v[198:201], v[88:91]
	v_mfma_f32_16x16x32_bf16 v[132:135], v[144:147], v[170:173], v[132:135]
	v_mfma_f32_16x16x32_bf16 v[128:131], v[158:161], v[170:173], v[128:131]
	v_mfma_f32_16x16x32_bf16 v[116:119], v[144:147], v[178:181], v[116:119]
	v_mfma_f32_16x16x32_bf16 v[112:115], v[158:161], v[178:181], v[112:115]
	v_mfma_f32_16x16x32_bf16 v[100:103], v[144:147], v[186:189], v[100:103]
	v_mfma_f32_16x16x32_bf16 v[96:99], v[158:161], v[186:189], v[96:99]
	v_mfma_f32_16x16x32_bf16 v[84:87], v[144:147], v[194:197], v[84:87]
	v_mfma_f32_16x16x32_bf16 v[80:83], v[158:161], v[194:197], v[80:83]
	v_mfma_f32_16x16x32_bf16 v[132:135], v[148:151], v[174:177], v[132:135]
	v_mfma_f32_16x16x32_bf16 v[128:131], v[162:165], v[174:177], v[128:131]
	v_mfma_f32_16x16x32_bf16 v[116:119], v[148:151], v[182:185], v[116:119]
	v_mfma_f32_16x16x32_bf16 v[112:115], v[162:165], v[182:185], v[112:115]
	v_mfma_f32_16x16x32_bf16 v[100:103], v[148:151], v[190:193], v[100:103]
	v_mfma_f32_16x16x32_bf16 v[96:99], v[162:165], v[190:193], v[96:99]
	v_mfma_f32_16x16x32_bf16 v[84:87], v[148:151], v[198:201], v[84:87]
	v_mfma_f32_16x16x32_bf16 v[80:83], v[162:165], v[198:201], v[80:83]
	s_barrier
; #define PG8_STAGE(bufoff, gbase, voff) do { _Pragma("unroll") for (int _i = 0; _i < 2; ++_i) \
;         __builtin_amdgcn_global_load_lds((const unsigned*)((const char*)(gbase) + (voff)[_i]), (LAS unsigned*)(lds + (bufoff) + ldsw + _i * 8192), 16, 0, 0); } while (0)
; #define PG8_LDA(dst, b, h) do { _Pragma("unroll") for (int m = 0; m < 4; ++m) _Pragma("unroll") for (int k = 0; k < 2; ++k) dst[m][k] = *(const LAS bf16x8*)(lds + PG8_SA(b, h) + aoff + m * 2048 + k * 1024); } while (0)
; #define PG8_MMA(ai, bj, At, Bt) do { __builtin_amdgcn_s_setprio(1); _Pragma("unroll") for (int m = 0; m < 4; ++m) _Pragma("unroll") for (int n = 0; n < 2; ++n) _Pragma("unroll") for (int k = 0; k < 2; ++k) \
;         acc[ai][bj][m][n] = __builtin_amdgcn_mfma_f32_16x16x32_bf16(Bt[n][k], At[m][k], acc[ai][bj][m][n], 0, 0, 0); __builtin_amdgcn_s_setprio(0); } while (0)
; #define PG8_WAIT_V(n) asm volatile("s_waitcnt vmcnt(" #n ")" ::: "memory")
; #define PG8_WAIT_L(n) asm volatile("s_waitcnt lgkmcnt(" #n ")" ::: "memory")
; #define PG8_BAR __builtin_amdgcn_s_barrier()
; #define PG8_SCHED __builtin_amdgcn_sched_barrier(0)
; template <class Epi, class Sched>
; DI void gemm_phase(LAS unsigned char* lds, const Gemm g, const Sched& S, const Epi& E) {
;     ...
;             PG8_LDA(At, 1, 1); PG8_STAGE(PG8_SB(1, 0), b3, voffB); PG8_STAGE(PG8_SB(1, 1), b3 + hstepB, voffB); PG8_STAGE(PG8_SA(1, 0), a3, voffA);
;             PG8_WAIT_V(8); PG8_WAIT_L(0); PG8_BAR; PG8_MMA(1, 0, At, B0); PG8_MMA(1, 1, At, B1); PG8_BAR; PG8_SCHED;
;         }
;         if (wr == 0) PG8_BAR;
	s_add_i32 s9, s9, s4
	v_lshl_add_u64 v[202:203], v[202:203], 0, s[28:29]
	s_mov_b32 m0, s9
	ds_read_b128 v[170:173], v169 offset:49152
	ds_read_b128 v[174:177], v169 offset:50176
	ds_read_b128 v[178:181], v169 offset:51200
	ds_read_b128 v[182:185], v169 offset:52224
	ds_read_b128 v[186:189], v169 offset:53248
	ds_read_b128 v[190:193], v169 offset:54272
	ds_read_b128 v[194:197], v169 offset:55296
	ds_read_b128 v[198:201], v169 offset:56320
	global_load_lds_dwordx4 v[202:203], off
	s_add_i32 m0, s9, 0x2000
	s_add_u32 s10, s68, 0x80080
	v_lshl_add_u64 v[202:203], v[204:205], 0, s[28:29]
	s_addc_u32 s11, s69, 0
	s_add_i32 s9, s12, s4
	global_load_lds_dwordx4 v[202:203], off
	v_lshl_add_u64 v[202:203], s[10:11], 0, v[222:223]
	s_mov_b32 m0, s9
	s_nop 0
	global_load_lds_dwordx4 v[202:203], off
	v_lshl_add_u64 v[202:203], s[10:11], 0, v[152:153]
	s_add_i32 m0, s9, 0x2000
	s_nop 0
	global_load_lds_dwordx4 v[202:203], off
	v_lshl_add_u64 v[202:203], v[206:207], 0, s[28:29]
	s_mov_b32 m0, s75
	s_nop 0
	global_load_lds_dwordx4 v[202:203], off
	v_lshl_add_u64 v[202:203], v[208:209], 0, s[28:29]
	s_mov_b32 m0, s89
	s_nop 0
	global_load_lds_dwordx4 v[202:203], off
	s_waitcnt vmcnt(8)
	s_waitcnt lgkmcnt(0)
	s_barrier
	s_waitcnt lgkmcnt(0)
	v_mfma_f32_16x16x32_bf16 v[76:79], v[56:59], v[170:173], v[76:79]
	v_mfma_f32_16x16x32_bf16 v[64:67], v[68:71], v[170:173], v[64:67]
	v_mfma_f32_16x16x32_bf16 v[44:47], v[56:59], v[178:181], v[44:47]
	v_mfma_f32_16x16x32_bf16 v[40:43], v[68:71], v[178:181], v[40:43]
	v_mfma_f32_16x16x32_bf16 v[28:31], v[56:59], v[186:189], v[28:31]
	v_mfma_f32_16x16x32_bf16 v[24:27], v[68:71], v[186:189], v[24:27]
	v_mfma_f32_16x16x32_bf16 v[12:15], v[56:59], v[194:197], v[12:15]
	v_mfma_f32_16x16x32_bf16 v[8:11], v[68:71], v[194:197], v[8:11]
	v_mfma_f32_16x16x32_bf16 v[76:79], v[60:63], v[174:177], v[76:79]
	v_mfma_f32_16x16x32_bf16 v[64:67], v[72:75], v[174:177], v[64:67]
	v_mfma_f32_16x16x32_bf16 v[44:47], v[60:63], v[182:185], v[44:47]
	v_mfma_f32_16x16x32_bf16 v[40:43], v[72:75], v[182:185], v[40:43]
	v_mfma_f32_16x16x32_bf16 v[28:31], v[60:63], v[190:193], v[28:31]
	v_mfma_f32_16x16x32_bf16 v[24:27], v[72:75], v[190:193], v[24:27]
	v_mfma_f32_16x16x32_bf16 v[12:15], v[60:63], v[198:201], v[12:15]
	v_mfma_f32_16x16x32_bf16 v[8:11], v[72:75], v[198:201], v[8:11]
	v_mfma_f32_16x16x32_bf16 v[52:55], v[144:147], v[170:173], v[52:55]
	v_mfma_f32_16x16x32_bf16 v[48:51], v[158:161], v[170:173], v[48:51]
	v_mfma_f32_16x16x32_bf16 v[36:39], v[144:147], v[178:181], v[36:39]
	v_mfma_f32_16x16x32_bf16 v[32:35], v[158:161], v[178:181], v[32:35]
	v_mfma_f32_16x16x32_bf16 v[20:23], v[144:147], v[186:189], v[20:23]
	v_mfma_f32_16x16x32_bf16 v[16:19], v[158:161], v[186:189], v[16:19]
	v_mfma_f32_16x16x32_bf16 v[4:7], v[144:147], v[194:197], v[4:7]
	v_mfma_f32_16x16x32_bf16 v[0:3], v[158:161], v[194:197], v[0:3]
	v_mfma_f32_16x16x32_bf16 v[52:55], v[148:151], v[174:177], v[52:55]
	v_mfma_f32_16x16x32_bf16 v[48:51], v[162:165], v[174:177], v[48:51]
	v_mfma_f32_16x16x32_bf16 v[36:39], v[148:151], v[182:185], v[36:39]
	v_mfma_f32_16x16x32_bf16 v[32:35], v[162:165], v[182:185], v[32:35]
	v_mfma_f32_16x16x32_bf16 v[20:23], v[148:151], v[190:193], v[20:23]
	v_mfma_f32_16x16x32_bf16 v[16:19], v[162:165], v[190:193], v[16:19]
	v_mfma_f32_16x16x32_bf16 v[4:7], v[148:151], v[198:201], v[4:7]
	v_mfma_f32_16x16x32_bf16 v[0:3], v[162:165], v[198:201], v[0:3]
	s_add_i32 s8, s8, 2
	s_add_u32 s66, s66, 0x100
	s_addc_u32 s67, s67, 0
	s_add_u32 s6, s6, 0x100
	s_addc_u32 s7, s7, 0
	s_barrier
	s_cmp_gt_u32 s8, 29
	s_cbranch_scc0 .LBB0_417
	s_and_b64 vcc, exec, s[18:19]
	s_cbranch_vccz .LBB0_420
	s_barrier
